# v15 + once-only dry pass for regions executed several times (p1gen, p5a, p5b) via v251 lane flags; new GPU container
# baseline (speedup 1.0000x reference)
; #define LAS __attribute__((address_space(3)))
; __global__ void __launch_bounds__(512, 2) mk_fwd(Args args) {
;     ...
;     const int lo = args.ph_lo, hi = args.ph_hi;
;     if (lo < 0) grid.sync();
;     if (tid < 16) ((LAS unsigned*)(lds + LDS_MISC))[tid] = 0u;
;     __syncthreads();
_Z6mk_fwd4Args:
	v_mov_b32_e32 v251, 0
	s_mov_b32 s99, 0
	s_load_dwordx4 s[68:71], s[0:1], 0x60
	s_load_dword s3, s[0:1], 0x70
	s_add_u32 s6, s0, 0x68
	s_addc_u32 s7, s1, 0
	v_and_b32_e32 v200, 0x3ff, v0
	s_waitcnt lgkmcnt(0)
	s_cmp_gt_i32 s68, -1
	v_writelane_b32 v250, s3, 0
	s_movk_i32 s3, 0x3ff
	s_cbranch_scc0 .LBB0_26
	s_load_dwordx8 s[60:67], s[0:1], 0x40
	v_cmp_gt_u32_e32 vcc, 16, v200
	s_and_saveexec_b64 s[4:5], vcc

; __device__ __forceinline__ unsigned cvt_pk_bf16(float lo, float hi) { f32x2_t v = {lo, hi}; bf16x2_t b = __builtin_convertvector(v, bf16x2_t); return __builtin_bit_cast(unsigned, b); }
; __device__ __forceinline__ float siluf_(float v) { return v * sigmoidf_(v); }
;     __device__ __forceinline__ void operator()(const f32x4 (&acc)[2][2][4][2], const pg8::Unit& u, int wr, int wc, int fr, int fq) const {
;     ...
;             bf16_t* base = seg == 0 ? sbq : seg == 1 ? sbk : seg == 2 ? sbv : seg == 4 ? hgq : hgi;
;             const float sc = seg == 0 ? 0.08838834764831845f : 1.f; const bool act = seg == 4;
; #pragma unroll
;             for (int ai = 0; ai < 2; ++ai)
; #pragma unroll
;                 for (int m = 0; m < 4; ++m)
; #pragma unroll
;                     for (int bj = 0; bj < 2; ++bj) {
;                         f32x4 a = acc[ai][bj][m][0], b = acc[ai][bj][m][1];
;                         if (act) {
; #pragma unroll
;                             for (int j = 0; j < 4; ++j) { a[j] = siluf_(a[j]); b[j] = siluf_(b[j]); } }
;                         a = a * sc; b = b * sc;
;                         u32x4 w; w.x = cvt_pk_bf16(a[0], a[1]); w.y = cvt_pk_bf16(a[2], a[3]); w.z = cvt_pk_bf16(b[0], b[1]); w.w = cvt_pk_bf16(b[2], b[3]);
;                         *(u32x4*)(base + (size_t)(row0 + ai * 128 + m * 16) * 1024 + col0 + bj * 128) = w;
;                     }
.LBB0_113:
	v_readlane_b32 s98, v251, 4
	s_nop 0
	s_cmp_lg_u32 s98, 0
	s_cbranch_scc1 .Ldry_p1gen_skip
	v_writelane_b32 v251, 1, 4
	s_mov_b64 s[100:101], s[4:5]
	v_readfirstlane_b32 s98, v200
	s_nop 0
	s_lshr_b32 s98, s98, 6
	s_cmp_eq_u32 s98, 0
	s_cbranch_scc1 .Ldry_p1gen_real
	s_mov_b64 exec, 0
	s_cmp_eq_u32 s98, 1
	s_cbranch_scc1 .Ldry_p1gen_c1
	s_cmp_eq_u32 s98, 2
	s_cbranch_scc1 .Ldry_p1gen_c2
	s_cmp_eq_u32 s98, 3
	s_cbranch_scc1 .Ldry_p1gen_c3
	s_cmp_eq_u32 s98, 4
	s_cbranch_scc1 .Ldry_p1gen_c4
	s_cmp_eq_u32 s98, 5
	s_cbranch_scc1 .Ldry_p1gen_c5
	s_cmp_eq_u32 s98, 6
	s_cbranch_scc1 .Ldry_p1gen_c6
	s_branch .Ldry_p1gen_c7
.Ldry_p1gen_real:
	s_mov_b64 exec, -1
	s_mov_b64 s[4:5], s[100:101]

; __device__ __forceinline__ unsigned cvt_pk_bf16(float lo, float hi) { f32x2_t v = {lo, hi}; bf16x2_t b = __builtin_convertvector(v, bf16x2_t); return __builtin_bit_cast(unsigned, b); }
; __device__ __forceinline__ float bf2f(unsigned u) { return __uint_as_float(u << 16); }
; __device__ __forceinline__ float siluf_(float v) { return v * sigmoidf_(v); }
;     __device__ __forceinline__ void operator()(const f32x4 (&acc)[2][2][4][2], const pg8::Unit& u, int wr, int wc, int fr, int fq) const {
;     ...
;             bf16_t* base = seg == 3 ? asb : ahg;
; #pragma unroll
;             for (int ai = 0; ai < 2; ++ai) {
;                 u32x4 ov[4][2];
; #pragma unroll
;                 for (int m = 0; m < 4; ++m)
; #pragma unroll
;                     for (int bj = 0; bj < 2; ++bj) ov[m][bj] = *(const u32x4*)(base + (size_t)(row0 + ai * 128 + m * 16) * 1024 + col0 + bj * 128);
; #pragma unroll
;                 for (int m = 0; m < 4; ++m)
; #pragma unroll
;                     for (int bj = 0; bj < 2; ++bj) {
;                         const u32x4 o = ov[m][bj];
;                         const f32x4 a = acc[ai][bj][m][0], b = acc[ai][bj][m][1];
;                         u32x4 w;
;                         w.x = cvt_pk_bf16(bf2f(o.x & 0xffffu) * siluf_(a[0]), bf2f(o.x >> 16) * siluf_(a[1]));
;                         w.y = cvt_pk_bf16(bf2f(o.y & 0xffffu) * siluf_(a[2]), bf2f(o.y >> 16) * siluf_(a[3]));
;                         w.z = cvt_pk_bf16(bf2f(o.z & 0xffffu) * siluf_(b[0]), bf2f(o.z >> 16) * siluf_(b[1]));
;                         w.w = cvt_pk_bf16(bf2f(o.w & 0xffffu) * siluf_(b[2]), bf2f(o.w >> 16) * siluf_(b[3]));
;                         *(u32x4*)(base + (size_t)(row0 + ai * 128 + m * 16) * 1024 + col0 + bj * 128) = w;
;                     }
.LBB0_527:
	v_lshl_add_u32 v176, s40, 8, v190
	s_lshl_b32 s3, s48, 8
	s_ashr_i32 s27, s48, 2
	s_and_b32 s3, s3, 0x300
	v_or_b32_e32 v174, 16, v176
	v_or_b32_e32 v172, 32, v176
	v_or_b32_e32 v170, 48, v176
	v_or_b32_e32 v196, s3, v192
	s_mov_b64 s[40:41], -1
	s_cmp_lt_i32 s27, 8
	v_ashrrev_i32_e32 v177, 31, v176
	v_ashrrev_i32_e32 v175, 31, v174
	v_ashrrev_i32_e32 v173, 31, v172
	v_ashrrev_i32_e32 v171, 31, v170
	s_cbranch_scc0 .LBB0_530
	v_readlane_b32 s98, v251, 5
	s_nop 0
	s_cmp_lg_u32 s98, 0
	s_cbranch_scc1 .Ldry_p5a_skip
	v_writelane_b32 v251, 1, 5
	v_readfirstlane_b32 s98, v200
	s_nop 0
	s_lshr_b32 s98, s98, 6
	s_cmp_eq_u32 s98, 0
	s_cbranch_scc1 .Ldry_p5a_real
	s_mov_b64 exec, 0
	s_cmp_eq_u32 s98, 1
	s_cbranch_scc1 .Ldry_p5a_c1
	s_cmp_eq_u32 s98, 2
	s_cbranch_scc1 .Ldry_p5a_c2
	s_cmp_eq_u32 s98, 3
	s_cbranch_scc1 .Ldry_p5a_c3
	s_cmp_eq_u32 s98, 4
	s_cbranch_scc1 .Ldry_p5a_c4
	s_cmp_eq_u32 s98, 5
	s_cbranch_scc1 .Ldry_p5a_c5
	s_cmp_eq_u32 s98, 6
	s_cbranch_scc1 .Ldry_p5a_c6
	s_branch .Ldry_p5a_c7
.Ldry_p5a_real:
	s_mov_b64 exec, -1
.Ldry_p5a_skip:
	v_readlane_b32 s12, v250, 17
	s_cmp_eq_u32 s27, 3
	v_readlane_b32 s13, v250, 18
	s_cselect_b32 s41, s77, s13
	s_cselect_b32 s40, s76, s12
	v_lshlrev_b32_e32 v160, 1, v196
	v_lshl_add_u64 v[128:129], s[40:41], 0, v[160:161]
	v_lshlrev_b64 v[130:131], 11, v[176:177]
	v_lshl_add_u64 v[178:179], v[128:129], 0, v[130:131]
	global_load_dwordx4 v[182:185], v[178:179], off
	global_load_dwordx4 v[186:189], v[178:179], off offset:256
	v_lshlrev_b64 v[130:131], 11, v[174:175]
	v_lshlrev_b64 v[132:133], 11, v[172:173]
	v_lshlrev_b64 v[134:135], 11, v[170:171]
	v_mul_f32_e32 v136, 0xbfb8aa3b, v124
	v_mul_f32_e32 v137, 0xbfb8aa3b, v125
	v_mul_f32_e32 v138, 0xbfb8aa3b, v126
	v_mul_f32_e32 v139, 0xbfb8aa3b, v127
	v_mul_f32_e32 v140, 0xbfb8aa3b, v120
	v_mul_f32_e32 v141, 0xbfb8aa3b, v121
	v_mul_f32_e32 v142, 0xbfb8aa3b, v122
	v_mul_f32_e32 v143, 0xbfb8aa3b, v123
	v_mul_f32_e32 v144, 0xbfb8aa3b, v60
	v_mul_f32_e32 v145, 0xbfb8aa3b, v61
	v_mul_f32_e32 v146, 0xbfb8aa3b, v62
	v_lshl_add_u64 v[180:181], v[128:129], 0, v[130:131]
	v_exp_f32_e32 v197, v136
	v_exp_f32_e32 v198, v137
	v_exp_f32_e32 v199, v138
	v_exp_f32_e32 v201, v139
	v_exp_f32_e32 v206, v140
	v_exp_f32_e32 v207, v141
	v_exp_f32_e32 v208, v142
	v_exp_f32_e32 v209, v143
	v_exp_f32_e32 v210, v144
	v_exp_f32_e32 v211, v145
	v_exp_f32_e32 v220, v146
	v_lshl_add_u64 v[150:151], v[128:129], 0, v[132:133]
	v_lshl_add_u64 v[148:149], v[128:129], 0, v[134:135]
	global_load_dwordx4 v[202:205], v[180:181], off
	global_load_dwordx4 v[144:147], v[180:181], off offset:256
	global_load_dwordx4 v[140:143], v[150:151], off
	global_load_dwordx4 v[136:139], v[150:151], off offset:256
	global_load_dwordx4 v[132:135], v[148:149], off
	global_load_dwordx4 v[128:131], v[148:149], off offset:256
	v_add_f32_e32 v197, 1.0, v197
	v_add_f32_e32 v212, 1.0, v198
	v_add_f32_e32 v213, 1.0, v199
	v_add_f32_e32 v201, 1.0, v201
	v_add_f32_e32 v214, 1.0, v206
	v_add_f32_e32 v215, 1.0, v207
	v_add_f32_e32 v216, 1.0, v208
	v_add_f32_e32 v217, 1.0, v209
	v_add_f32_e32 v218, 1.0, v210
	v_add_f32_e32 v219, 1.0, v211
	v_rcp_f32_e32 v198, v197
	v_rcp_f32_e32 v199, v212
	v_rcp_f32_e32 v206, v213
	v_rcp_f32_e32 v207, v201
	v_rcp_f32_e32 v208, v214
	v_rcp_f32_e32 v209, v215
	v_rcp_f32_e32 v210, v216
	v_rcp_f32_e32 v211, v217
	v_mul_f32_e32 v160, 0xbfb8aa3b, v63
	v_rcp_f32_e32 v212, v218
	v_rcp_f32_e32 v213, v219
	v_exp_f32_e32 v160, v160
	v_pk_mul_f32 v[198:199], v[124:125], v[198:199]
	v_pk_mul_f32 v[206:207], v[126:127], v[206:207]
	v_pk_mul_f32 v[208:209], v[120:121], v[208:209]
	v_pk_mul_f32 v[210:211], v[122:123], v[210:211]
	v_pk_mul_f32 v[212:213], v[60:61], v[212:213]
	v_add_f32_e32 v160, 1.0, v160
	s_mov_b32 s3, 0x40000
	s_mov_b64 s[40:41], 0x40000
	v_mul_f32_e32 v197, 0xbfb8aa3b, v95
	v_exp_f32_e32 v197, v197
	s_mov_b64 s[12:13], 0x58000
	s_waitcnt vmcnt(0)
	v_lshlrev_b32_e32 v214, 16, v182
	v_and_b32_e32 v215, 0xffff0000, v182
	v_lshlrev_b32_e32 v182, 16, v183
	v_and_b32_e32 v183, 0xffff0000, v183
	v_lshlrev_b32_e32 v216, 16, v184
	v_and_b32_e32 v217, 0xffff0000, v184
	v_lshlrev_b32_e32 v184, 16, v185
	v_and_b32_e32 v185, 0xffff0000, v185
	v_pk_mul_f32 v[198:199], v[198:199], v[214:215]
	v_pk_mul_f32 v[206:207], v[206:207], v[182:183]
	v_pk_mul_f32 v[208:209], v[208:209], v[216:217]
	v_pk_mul_f32 v[210:211], v[210:211], v[184:185]
	v_lshlrev_b32_e32 v218, 16, v186
	v_and_b32_e32 v219, 0xffff0000, v186
	v_cvt_pk_bf16_f32 v182, v198, v199
	v_cvt_pk_bf16_f32 v183, v206, v207
	v_cvt_pk_bf16_f32 v184, v208, v209
	v_cvt_pk_bf16_f32 v185, v210, v211
	global_store_dwordx4 v[178:179], v[182:185], off
	v_lshlrev_b32_e32 v186, 16, v187
	v_and_b32_e32 v187, 0xffff0000, v187
	v_pk_mul_f32 v[182:183], v[212:213], v[218:219]
	v_add_f32_e32 v184, 1.0, v220
	v_rcp_f32_e32 v185, v160
	v_mul_f32_e32 v160, 0xbfb8aa3b, v56
	v_rcp_f32_e32 v184, v184
	v_cvt_pk_bf16_f32 v182, v182, v183
	v_exp_f32_e32 v160, v160
	v_mul_f32_e32 v183, 0xbfb8aa3b, v57
	v_exp_f32_e32 v183, v183
	v_pk_mul_f32 v[184:185], v[62:63], v[184:185]
	v_add_f32_e32 v160, 1.0, v160
	v_pk_mul_f32 v[184:185], v[184:185], v[186:187]
	v_rcp_f32_e32 v186, v160
	v_add_f32_e32 v160, 1.0, v183
	s_cbranch_execz .Ldry_p5a_real

; __device__ __forceinline__ unsigned cvt_pk_bf16(float lo, float hi) { f32x2_t v = {lo, hi}; bf16x2_t b = __builtin_convertvector(v, bf16x2_t); return __builtin_bit_cast(unsigned, b); }
; __device__ __forceinline__ float sigmoidf_(float v) { return __builtin_amdgcn_rcpf(1.f + __expf(-v)); }
;     __device__ __forceinline__ void operator()(const f32x4 (&acc)[2][2][4][2], const pg8::Unit& u, int wr, int wc, int fr, int fq) const {
;     ...
;         if (seg >= 8) {
; #pragma unroll
;             for (int bj = 0; bj < 2; ++bj) {
;                 const int col = (seg - 8) * 1024 + col0 + bj * 128;
;                 const f32x4 b0 = *(const f32x4*)(bgate + col), b1 = *(const f32x4*)(bgate + col + 4);
; #pragma unroll
;                 for (int ai = 0; ai < 2; ++ai)
; #pragma unroll
;                     for (int m = 0; m < 4; ++m) {
;                         f32x4 a = acc[ai][bj][m][0] + b0, b = acc[ai][bj][m][1] + b1;
; #pragma unroll
;                         for (int j = 0; j < 4; ++j) { a[j] = sigmoidf_(a[j]); b[j] = sigmoidf_(b[j]); }
;                         u32x4 w; w.x = cvt_pk_bf16(a[0], a[1]); w.y = cvt_pk_bf16(a[2], a[3]); w.z = cvt_pk_bf16(b[0], b[1]); w.w = cvt_pk_bf16(b[2], b[3]);
;                         *(u32x4*)(gates + (size_t)(row0 + ai * 128 + m * 16) * 2048 + col) = w;
;                     }
;             }
.LBB0_531:
	v_readlane_b32 s98, v251, 6
	s_nop 0
	s_cmp_lg_u32 s98, 0
	s_cbranch_scc1 .Ldry_p5b_skip
	v_writelane_b32 v251, 1, 6
	s_mov_b64 s[100:101], s[26:27]
	v_readfirstlane_b32 s98, v200
	s_nop 0
	s_lshr_b32 s98, s98, 6
	s_cmp_eq_u32 s98, 0
	s_cbranch_scc1 .Ldry_p5b_real
	s_mov_b64 exec, 0
	s_cmp_eq_u32 s98, 1
	s_cbranch_scc1 .Ldry_p5b_c1
	s_cmp_eq_u32 s98, 2
	s_cbranch_scc1 .Ldry_p5b_c2
	s_cmp_eq_u32 s98, 3
	s_cbranch_scc1 .Ldry_p5b_c3
	s_cmp_eq_u32 s98, 4
	s_cbranch_scc1 .Ldry_p5b_c4
	s_cmp_eq_u32 s98, 5
	s_cbranch_scc1 .Ldry_p5b_c5
	s_cmp_eq_u32 s98, 6
	s_cbranch_scc1 .Ldry_p5b_c6
	s_branch .Ldry_p5b_c7
.Ldry_p5b_real:
	s_mov_b64 exec, -1
	s_mov_b64 s[26:27], s[100:101]
.Ldry_p5b_skip:
	s_lshl_b32 s3, s27, 10
	s_addk_i32 s3, 0xe000
	v_readlane_b32 s12, v250, 1
	v_or_b32_e32 v160, s3, v196
	v_readlane_b32 s18, v250, 7
	v_readlane_b32 s19, v250, 8
	v_lshlrev_b64 v[136:137], 12, v[176:177]
	v_lshlrev_b64 v[140:141], 12, v[174:175]
	v_lshl_add_u64 v[138:139], v[160:161], 2, s[18:19]
	global_load_dwordx4 v[132:135], v[138:139], off
	global_load_dwordx4 v[128:131], v[138:139], off offset:16
	v_lshl_add_u64 v[136:137], s[72:73], 0, v[136:137]
	v_lshl_add_u64 v[142:143], s[72:73], 0, v[140:141]
	v_lshlrev_b64 v[144:145], 1, v[160:161]
	v_lshl_add_u64 v[140:141], v[136:137], 0, v[144:145]
	v_lshl_add_u64 v[136:137], v[142:143], 0, v[144:145]
	s_mov_b32 s3, 0x80000
	v_readlane_b32 s13, v250, 2
	s_mov_b64 s[12:13], 0x90000
	v_readlane_b32 s14, v250, 3
	v_readlane_b32 s15, v250, 4
	v_readlane_b32 s16, v250, 5
	v_readlane_b32 s17, v250, 6
	v_readlane_b32 s20, v250, 9
	v_readlane_b32 s21, v250, 10
	v_readlane_b32 s22, v250, 11
	v_readlane_b32 s23, v250, 12
	v_readlane_b32 s24, v250, 13
	v_readlane_b32 s25, v250, 14
	v_readlane_b32 s26, v250, 15
	v_readlane_b32 s27, v250, 16
	s_waitcnt vmcnt(0)
	v_pk_add_f32 v[126:127], v[126:127], v[134:135]
	v_pk_add_f32 v[124:125], v[124:125], v[132:133]
	v_pk_add_f32 v[122:123], v[122:123], v[130:131]
	v_pk_add_f32 v[120:121], v[120:121], v[128:129]
	v_pk_add_f32 v[118:119], v[118:119], v[134:135]
	v_pk_add_f32 v[116:117], v[116:117], v[132:133]
	v_pk_add_f32 v[114:115], v[114:115], v[130:131]
	v_pk_add_f32 v[112:113], v[112:113], v[128:129]
	v_pk_add_f32 v[142:143], v[110:111], v[134:135]
	v_pk_add_f32 v[146:147], v[108:109], v[132:133]
	v_mul_f32_e32 v108, 0xbfb8aa3b, v124
	v_mul_f32_e32 v109, 0xbfb8aa3b, v120
	v_mul_f32_e32 v110, 0xbfb8aa3b, v125
	v_mul_f32_e32 v111, 0xbfb8aa3b, v121
	v_mul_f32_e32 v120, 0xbfb8aa3b, v126
	v_mul_f32_e32 v121, 0xbfb8aa3b, v122
	v_mul_f32_e32 v122, 0xbfb8aa3b, v127
	v_mul_f32_e32 v123, 0xbfb8aa3b, v123
	v_mul_f32_e32 v116, 0xbfb8aa3b, v116
	v_mul_f32_e32 v112, 0xbfb8aa3b, v112
	v_mul_f32_e32 v117, 0xbfb8aa3b, v117
	v_mul_f32_e32 v113, 0xbfb8aa3b, v113
	v_mul_f32_e32 v118, 0xbfb8aa3b, v118
	v_mul_f32_e32 v114, 0xbfb8aa3b, v114
	v_mul_f32_e32 v119, 0xbfb8aa3b, v119
	v_mul_f32_e32 v115, 0xbfb8aa3b, v115
	v_exp_f32_e32 v108, v108
	v_exp_f32_e32 v109, v109
	v_exp_f32_e32 v110, v110
	v_exp_f32_e32 v111, v111
	v_exp_f32_e32 v120, v120
	v_exp_f32_e32 v121, v121
	v_exp_f32_e32 v122, v122
	v_exp_f32_e32 v123, v123
	v_exp_f32_e32 v116, v116
	v_exp_f32_e32 v112, v112
	v_exp_f32_e32 v117, v117
	v_exp_f32_e32 v113, v113
	v_exp_f32_e32 v118, v118
	v_exp_f32_e32 v114, v114
	v_exp_f32_e32 v119, v119
	v_exp_f32_e32 v115, v115
	v_add_f32_e32 v108, 1.0, v108
	v_add_f32_e32 v109, 1.0, v109
	v_add_f32_e32 v110, 1.0, v110
	v_add_f32_e32 v111, 1.0, v111
	v_add_f32_e32 v120, 1.0, v120
	v_add_f32_e32 v121, 1.0, v121
	v_add_f32_e32 v122, 1.0, v122
	v_add_f32_e32 v123, 1.0, v123
	v_add_f32_e32 v116, 1.0, v116
	v_add_f32_e32 v112, 1.0, v112
	v_add_f32_e32 v117, 1.0, v117
	v_add_f32_e32 v113, 1.0, v113
	v_add_f32_e32 v118, 1.0, v118
	v_add_f32_e32 v114, 1.0, v114
	v_add_f32_e32 v119, 1.0, v119
	s_cbranch_execz .Ldry_p5b_real

; __global__ void __launch_bounds__(512, 2) mk_fwd(Args args) {
	.amdhsa_kernel _Z6mk_fwd4Args
		.amdhsa_group_segment_fixed_size 0
		.amdhsa_private_segment_fixed_size 0
		.amdhsa_kernarg_size 360
		.amdhsa_user_sgpr_count 2
		.amdhsa_user_sgpr_dispatch_ptr 0
		.amdhsa_user_sgpr_queue_ptr 0
		.amdhsa_user_sgpr_kernarg_segment_ptr 1
		.amdhsa_user_sgpr_dispatch_id 0
		.amdhsa_user_sgpr_kernarg_preload_length 0
		.amdhsa_user_sgpr_kernarg_preload_offset 0
		.amdhsa_user_sgpr_private_segment_size 0
		.amdhsa_uses_dynamic_stack 0
		.amdhsa_enable_private_segment 0
		.amdhsa_system_sgpr_workgroup_id_x 1
		.amdhsa_system_sgpr_workgroup_id_y 0
		.amdhsa_system_sgpr_workgroup_id_z 0
		.amdhsa_system_sgpr_workgroup_info 0
		.amdhsa_system_vgpr_workitem_id 2
		.amdhsa_next_free_vgpr 252
		.amdhsa_next_free_sgpr 102
		.amdhsa_accum_offset 252
		.amdhsa_reserve_vcc 1
		.amdhsa_float_round_mode_32 0
		.amdhsa_float_round_mode_16_64 0
		.amdhsa_float_denorm_mode_32 3
		.amdhsa_float_denorm_mode_16_64 3
		.amdhsa_dx10_clamp 1
		.amdhsa_ieee_mode 1
		.amdhsa_fp16_overflow 0
		.amdhsa_tg_split 0
		.amdhsa_exception_fp_ieee_invalid_op 0
		.amdhsa_exception_fp_denorm_src 0
		.amdhsa_exception_fp_ieee_div_zero 0
		.amdhsa_exception_fp_ieee_overflow 0
		.amdhsa_exception_fp_ieee_underflow 0
		.amdhsa_exception_fp_ieee_inexact 0
		.amdhsa_exception_int_div_zero 0
	.end_amdhsa_kernel

; __global__ void __launch_bounds__(512, 2) mk_fwd(Args args) {
amdhsa.kernels:
  - .agpr_count:     0
    .args:
      - .offset:         0
        .size:           104
        .value_kind:     by_value
      - .offset:         104
        .size:           4
        .value_kind:     hidden_block_count_x
      - .offset:         108
        .size:           4
        .value_kind:     hidden_block_count_y
      - .offset:         112
        .size:           4
        .value_kind:     hidden_block_count_z
      - .offset:         116
        .size:           2
        .value_kind:     hidden_group_size_x
      - .offset:         118
        .size:           2
        .value_kind:     hidden_group_size_y
      - .offset:         120
        .size:           2
        .value_kind:     hidden_group_size_z
      - .offset:         122
        .size:           2
        .value_kind:     hidden_remainder_x
      - .offset:         124
        .size:           2
        .value_kind:     hidden_remainder_y
      - .offset:         126
        .size:           2
        .value_kind:     hidden_remainder_z
      - .offset:         144
        .size:           8
        .value_kind:     hidden_global_offset_x
      - .offset:         152
        .size:           8
        .value_kind:     hidden_global_offset_y
      - .offset:         160
        .size:           8
        .value_kind:     hidden_global_offset_z
      - .offset:         168
        .size:           2
        .value_kind:     hidden_grid_dims
      - .offset:         192
        .size:           8
        .value_kind:     hidden_multigrid_sync_arg
      - .offset:         224
        .size:           4
        .value_kind:     hidden_dynamic_lds_size
    .group_segment_fixed_size: 0
    .kernarg_segment_align: 8
    .kernarg_segment_size: 360
    .language:       OpenCL C
    .language_version:
      - 2
      - 0
    .max_flat_workgroup_size: 512
    .name:           _Z6mk_fwd4Args
    .private_segment_fixed_size: 0
    .sgpr_count:     108
    .sgpr_spill_count: 26
    .symbol:         _Z6mk_fwd4Args.kd
    .uniform_work_group_size: 1
    .uses_dynamic_stack: false
    .vgpr_count:     252
    .vgpr_spill_count: 0
    .wavefront_size: 64
